# stack + near-tile bias v_pk_add_f32 split into scalar adds (bit-identical)
# speedup vs baseline: 1.0024x; 1.0024x over previous
.LBB0_336:
	v_mov_b32_e32 v52, v162
	v_mov_b32_e32 v123, v99
	v_ashrrev_i32_e32 v50, 4, v52
	v_lshlrev_b32_e32 v20, 3, v52
	v_add_u32_e32 v21, 32, v50
	v_and_b32_e32 v24, 0x78, v20
	v_mad_i64_i32 v[2:3], s[12:13], v50, s52, 0
	v_mad_i64_i32 v[4:5], s[12:13], v21, s52, 0
	v_or_b32_e32 v2, v2, v24
	v_or_b32_e32 v4, v4, v24
	v_lshlrev_b64 v[10:11], 1, v[2:3]
	v_lshlrev_b64 v[12:13], 1, v[4:5]
	v_lshl_add_u64 v[2:3], s[36:37], 0, v[10:11]
	v_lshl_add_u64 v[6:7], s[36:37], 0, v[12:13]
	v_lshl_add_u64 v[10:11], s[34:35], 0, v[10:11]
	v_lshl_add_u64 v[14:15], s[34:35], 0, v[12:13]
	global_load_dwordx4 v[2:5], v[2:3], off
	s_nop 0
	global_load_dwordx4 v[6:9], v[6:7], off
	s_nop 0
	global_load_dwordx4 v[10:13], v[10:11], off
	s_nop 0
	global_load_dwordx4 v[14:17], v[14:15], off
	s_lshl_b32 s12, s8, 7
	s_add_u32 s8, s76, s12
	s_addc_u32 s9, s77, 0
	v_ashrrev_i32_e32 v26, 1, v52
	v_bfe_u32 v51, v52, 5, 1
	v_bfi_b32 v23, s18, v26, v52
	v_mov_b64_e32 v[18:19], s[8:9]
	v_bfe_u32 v27, v20, 5, 2
	v_lshlrev_b32_e32 v28, 5, v50
	v_and_b32_e32 v20, 24, v20
	v_add_u32_e32 v30, 64, v50
	v_lshrrev_b32_e32 v22, 5, v52
	v_lshlrev_b32_e32 v98, 4, v51
	v_add_u32_e32 v31, 0x60, v50
	v_mad_i64_i32 v[18:19], s[8:9], v23, s49, v[18:19]
	v_and_or_b32 v28, v28, s51, v20
	v_lshrrev_b32_e32 v33, 1, v21
	v_lshlrev_b32_e32 v35, 8, v21
	v_mad_i64_i32 v[20:21], s[8:9], v30, s52, 0
	v_and_or_b32 v32, v22, s50, v27
	v_mad_i64_i32 v[22:23], s[8:9], v31, s52, 0
	v_lshl_add_u64 v[18:19], v[18:19], 0, v[98:99]
	v_lshlrev_b32_e32 v28, 1, v28
	v_or_b32_e32 v20, v20, v24
	v_and_b32_e32 v25, 0x70, v52
	v_lshlrev_b32_e32 v29, 8, v50
	v_lshlrev_b32_e32 v34, 1, v24
	v_and_or_b32 v27, v33, s50, v27
	v_or_b32_e32 v22, v22, v24
	global_load_dwordx4 v[118:121], v[18:19], off
	global_load_dwordx4 v[114:117], v[18:19], off offset:32
	global_load_dwordx4 v[110:113], v[18:19], off offset:64
	global_load_dwordx4 v[106:109], v[18:19], off offset:96
	v_lshl_or_b32 v24, v32, 9, v28
	v_lshlrev_b64 v[18:19], 1, v[20:21]
	v_bitop3_b32 v29, v34, v29, v25 bitop3:0xde
	v_bitop3_b32 v25, v34, v35, v25 bitop3:0xde
	v_lshl_or_b32 v27, v27, 9, v28
	v_lshlrev_b64 v[20:21], 1, v[22:23]
	v_add_u32_e32 v183, 0, v24
	v_lshl_add_u64 v[22:23], s[36:37], 0, v[18:19]
	v_add_u32_e32 v181, 0, v29
	v_add_u32_e32 v182, 0, v25
	v_add_u32_e32 v184, 0, v27
	v_lshl_add_u64 v[24:25], s[36:37], 0, v[20:21]
	v_lshl_add_u64 v[18:19], s[34:35], 0, v[18:19]
	v_lshl_add_u64 v[20:21], s[34:35], 0, v[20:21]
	global_load_dwordx4 v[34:37], v[22:23], off
	global_load_dwordx4 v[38:41], v[24:25], off
	global_load_dwordx4 v[42:45], v[18:19], off
	global_load_dwordx4 v[46:49], v[20:21], off
	s_waitcnt vmcnt(0)
	v_and_b32_e32 v55, 63, v52
	v_and_b32_e32 v54, 0xffffffe0, v26
	v_and_b32_e32 v53, 31, v52
	v_add_u32_e32 v185, s75, v54
	v_cmp_gt_u32_e32 vcc, 32, v55
	v_or_b32_e32 v178, v185, v53
	v_mov_b32_e32 v124, v99
	v_cndmask_b32_e32 v122, 0, v170, vcc
	v_mov_b32_e32 v125, v99
	s_barrier
	s_waitcnt vmcnt(7)
	ds_write_b128 v183, v[2:5]
	s_waitcnt vmcnt(6)
	ds_write_b128 v184, v[6:9]
	s_waitcnt vmcnt(5)
	ds_write_b128 v181, v[10:13] offset:32768
	s_waitcnt vmcnt(4)
	ds_write_b128 v182, v[14:17] offset:32768
	s_waitcnt lgkmcnt(0)
	s_barrier
	ds_read_b32 v2, v173
	ds_read_b32 v3, v171
	s_waitcnt lgkmcnt(1)
	v_readfirstlane_b32 s43, v2
	s_waitcnt lgkmcnt(0)
	v_readfirstlane_b32 s42, v3
	v_lshlrev_b32_e32 v18, 4, v52
	v_mfma_f32_32x32x16_bf16 v[2:17], v[122:125], v[102:105], 0
	v_lshlrev_b32_e32 v64, 8, v53
	v_and_b32_e32 v65, 0x70, v18
	s_add_i32 s8, s12, 0
	v_bitop3_b32 v18, v98, v64, v65 bitop3:0xde
	v_add_u32_e32 v186, s8, v18
	ds_read_b128 v[56:59], v186 offset:32768
	ds_read_b128 v[60:63], v186 offset:40960
	v_lshlrev_b32_e32 v179, 2, v51
	s_waitcnt vmcnt(7) lgkmcnt(1)
	v_mfma_f32_32x32x16_bf16 v[18:33], v[56:59], v[118:121], v[2:17]
	v_or_b32_e32 v56, 32, v98
	v_bitop3_b32 v56, v56, v64, v65 bitop3:0xde
	v_add_u32_e32 v187, s8, v56
	s_waitcnt lgkmcnt(0)
	v_mfma_f32_32x32x16_bf16 v[2:17], v[60:63], v[118:121], v[2:17]
	ds_read_b128 v[56:59], v187 offset:32768
	ds_read_b128 v[60:63], v187 offset:40960
	s_waitcnt vmcnt(6) lgkmcnt(1)
	v_mfma_f32_32x32x16_bf16 v[18:33], v[56:59], v[114:117], v[18:33]
	v_or_b32_e32 v56, 64, v98
	v_bitop3_b32 v56, v56, v64, v65 bitop3:0xde
	v_add_u32_e32 v188, s8, v56
	s_waitcnt lgkmcnt(0)
	v_mfma_f32_32x32x16_bf16 v[2:17], v[60:63], v[114:117], v[2:17]
	ds_read_b128 v[56:59], v188 offset:32768
	ds_read_b128 v[60:63], v188 offset:40960
	s_waitcnt vmcnt(5) lgkmcnt(1)
	v_mfma_f32_32x32x16_bf16 v[18:33], v[56:59], v[110:113], v[18:33]
	v_or_b32_e32 v56, 0x60, v98
	v_bitop3_b32 v56, v56, v64, v65 bitop3:0xde
	v_add_u32_e32 v189, s8, v56
	s_waitcnt lgkmcnt(0)
	v_mfma_f32_32x32x16_bf16 v[2:17], v[60:63], v[110:113], v[2:17]
	ds_read_b128 v[56:59], v189 offset:32768
	ds_read_b128 v[60:63], v189 offset:40960
	s_waitcnt vmcnt(4) lgkmcnt(1)
	v_mfma_f32_32x32x16_bf16 v[18:33], v[56:59], v[106:109], v[18:33]
	v_add_u32_e32 v56, 0x9e, v185
	v_cmp_gt_u32_e64 s[8:9], s53, v56
	s_waitcnt lgkmcnt(0)
	v_mfma_f32_32x32x16_bf16 v[2:17], v[60:63], v[106:109], v[2:17]
	s_and_saveexec_b64 s[12:13], s[8:9]
	s_cbranch_execz .LBB0_338
	v_sub_u32_e32 v51, v179, v178
	v_lshl_add_u32 v51, v51, 2, s1
	ds_read2_b32 v[56:57], v51 offset0:240 offset1:241
	ds_read2_b32 v[58:59], v51 offset0:242 offset1:243
	ds_read2_b32 v[60:61], v51 offset0:248 offset1:249
	ds_read2_b32 v[62:63], v51 offset0:250 offset1:251
	ds_read2_b32 v[64:65], v51 offset0:224 offset1:225
	ds_read2_b32 v[66:67], v51 offset0:226 offset1:227
	ds_read2_b32 v[68:69], v51 offset0:232 offset1:233
	ds_read2_b32 v[70:71], v51 offset0:234 offset1:235
	s_waitcnt lgkmcnt(4)
	v_add_f32_e32 v32, v32, v62
	v_add_f32_e32 v33, v33, v63
	v_add_f32_e32 v30, v30, v60
	v_add_f32_e32 v31, v31, v61
	v_add_f32_e32 v28, v28, v58
	v_add_f32_e32 v29, v29, v59
	v_add_f32_e32 v26, v26, v56
	v_add_f32_e32 v27, v27, v57
	s_waitcnt lgkmcnt(0)
	v_add_f32_e32 v24, v24, v70
	v_add_f32_e32 v25, v25, v71
	v_add_f32_e32 v22, v22, v68
	v_add_f32_e32 v23, v23, v69
	v_add_f32_e32 v20, v20, v66
	v_add_f32_e32 v21, v21, v67
	v_add_f32_e32 v18, v18, v64
	v_add_f32_e32 v19, v19, v65
	v_add_u32_e32 v64, 0x400, v51
	v_add_u32_e32 v66, 0x408, v51
	v_add_u32_e32 v68, 0x420, v51
	v_add_u32_e32 v70, 0x428, v51
	v_add_u32_e32 v56, 0x440, v51
	v_add_u32_e32 v58, 0x448, v51
	v_add_u32_e32 v60, 0x460, v51
	v_add_u32_e32 v51, 0x468, v51
	ds_read2_b32 v[56:57], v56 offset1:1
	ds_read2_b32 v[58:59], v58 offset1:1
	ds_read2_b32 v[60:61], v60 offset1:1
	ds_read2_b32 v[62:63], v51 offset1:1
	ds_read2_b32 v[64:65], v64 offset1:1
	ds_read2_b32 v[66:67], v66 offset1:1
	ds_read2_b32 v[68:69], v68 offset1:1
	ds_read2_b32 v[70:71], v70 offset1:1
	s_waitcnt lgkmcnt(4)
	v_add_f32_e32 v16, v16, v62
	v_add_f32_e32 v17, v17, v63
	v_add_f32_e32 v14, v14, v60
	v_add_f32_e32 v15, v15, v61
	v_add_f32_e32 v12, v12, v58
	v_add_f32_e32 v13, v13, v59
	v_add_f32_e32 v10, v10, v56
	v_add_f32_e32 v11, v11, v57
	s_waitcnt lgkmcnt(0)
	v_add_f32_e32 v8, v8, v70
	v_add_f32_e32 v9, v9, v71
	v_add_f32_e32 v6, v6, v68
	v_add_f32_e32 v7, v7, v69
	v_add_f32_e32 v4, v4, v66
	v_add_f32_e32 v5, v5, v67
	v_add_f32_e32 v2, v2, v64
	v_add_f32_e32 v3, v3, v65

.Lattn_back_a:
	ds_read_b128 v[126:129], v186 offset:49152
	ds_read_b128 v[130:133], v186 offset:57344
	v_add_f32_e32 v98, 0, v199
	v_add_f32_e32 v98, v201, v98
	v_add_f32_e32 v98, v202, v98
	v_add_f32_e32 v98, v205, v98
	v_add_f32_e32 v98, v207, v98
	v_add_f32_e32 v98, v209, v98
	s_waitcnt lgkmcnt(1)
	v_mfma_f32_32x32x16_bf16 v[82:97], v[126:129], v[118:121], v[236:251]
	v_add_f32_e32 v98, v211, v98
	v_add_f32_e32 v98, v213, v98
	v_add_f32_e32 v98, v215, v98
	ds_read_b128 v[134:137], v187 offset:49152
	ds_read_b128 v[138:141], v187 offset:57344
	ds_read_b128 v[142:145], v188 offset:49152
	ds_read_b128 v[146:149], v188 offset:57344
	ds_read_b128 v[154:157], v189 offset:49152
	ds_read_b128 v[226:229], v189 offset:57344
	v_add_f32_e32 v98, v216, v98
	v_add_f32_e32 v98, v217, v98
	v_add_f32_e32 v98, v218, v98
	s_waitcnt lgkmcnt(6)
	v_mfma_f32_32x32x16_bf16 v[66:81], v[130:133], v[118:121], v[236:251]
	v_add_f32_e32 v98, v221, v98
	v_add_f32_e32 v98, v222, v98
	v_add_f32_e32 v98, v223, v98
	v_add_f32_e32 v98, v224, v98
	v_add_f32_e32 v98, v195, v98
	v_add_f32_e32 v98, v196, v98
	v_add_f32_e32 v98, v197, v98
	s_waitcnt lgkmcnt(5)
	v_mfma_f32_32x32x16_bf16 v[82:97], v[134:137], v[114:117], v[82:97]
	v_add_f32_e32 v98, v198, v98
	v_add_f32_e32 v98, v200, v98
	v_add_f32_e32 v98, v203, v98
	v_add_f32_e32 v98, v204, v98
	v_add_f32_e32 v98, v206, v98
	v_add_f32_e32 v98, v208, v98
	v_add_f32_e32 v98, v210, v98
	s_waitcnt lgkmcnt(4)
	v_mfma_f32_32x32x16_bf16 v[66:81], v[138:141], v[114:117], v[66:81]
	v_add_f32_e32 v98, v212, v98
	v_add_f32_e32 v98, v214, v98
	v_add_f32_e32 v98, v150, v98
	v_add_f32_e32 v98, v151, v98
	v_add_f32_e32 v98, v152, v98
	v_add_f32_e32 v219, v153, v98
	s_waitcnt lgkmcnt(3)
	v_mfma_f32_32x32x16_bf16 v[82:97], v[142:145], v[110:113], v[82:97]
	v_cvt_pk_bf16_f32 v134, v199, v201
	v_cvt_pk_bf16_f32 v135, v202, v205
	v_cvt_pk_bf16_f32 v136, v207, v209
	v_cvt_pk_bf16_f32 v137, v211, v213
	v_cvt_pk_bf16_f32 v138, v215, v216
	s_waitcnt lgkmcnt(2)
	v_mfma_f32_32x32x16_bf16 v[66:81], v[146:149], v[110:113], v[66:81]
	v_cvt_pk_bf16_f32 v139, v217, v218
	v_cvt_pk_bf16_f32 v140, v221, v222
	v_cvt_pk_bf16_f32 v141, v223, v224
	v_cvt_pk_bf16_f32 v126, v195, v196
	v_cvt_pk_bf16_f32 v127, v197, v198
	v_cvt_pk_bf16_f32 v128, v200, v203
	v_cvt_pk_bf16_f32 v129, v204, v206
	s_waitcnt lgkmcnt(1)
	v_mfma_f32_32x32x16_bf16 v[82:97], v[154:157], v[106:109], v[82:97]
	v_cvt_pk_bf16_f32 v130, v208, v210
	v_cvt_pk_bf16_f32 v131, v212, v214
	v_cvt_pk_bf16_f32 v132, v150, v151
	v_cvt_pk_bf16_f32 v133, v152, v153
	s_waitcnt lgkmcnt(0)
	v_mfma_f32_32x32x16_bf16 v[66:81], v[226:229], v[106:109], v[66:81]
	global_load_dwordx4 v[142:145], v160, s[12:13] offset:2048
	global_load_dwordx4 v[146:149], v252, s[12:13]
	global_load_dwordx4 v[154:157], v161, s[12:13] offset:2048
	s_and_saveexec_b64 s[2:3], s[8:9]
	s_cbranch_execz .LBB0_348
	ds_read2_b32 v[196:197], v194 offset1:1
	ds_read2_b32 v[198:199], v194 offset0:16 offset1:17
	ds_read2_b32 v[200:201], v194 offset0:18 offset1:19
	ds_read2_b32 v[202:203], v194 offset0:24 offset1:25
	ds_read2_b32 v[204:205], v194 offset0:26 offset1:27
	ds_read2_b32 v[206:207], v194 offset0:2 offset1:3
	ds_read2_b32 v[208:209], v194 offset0:8 offset1:9
	ds_read2_b32 v[210:211], v194 offset0:10 offset1:11
	s_waitcnt lgkmcnt(7)
	v_add_f32_e32 v82, v82, v196
	v_add_f32_e32 v83, v83, v197
	s_waitcnt lgkmcnt(3)
	v_add_f32_e32 v96, v96, v204
	v_add_f32_e32 v97, v97, v205
	v_add_f32_e32 v94, v94, v202
	v_add_f32_e32 v95, v95, v203
	v_add_f32_e32 v92, v92, v200
	v_add_f32_e32 v93, v93, v201
	v_add_f32_e32 v90, v90, v198
	v_add_f32_e32 v91, v91, v199
	s_waitcnt lgkmcnt(0)
	v_add_f32_e32 v88, v88, v210
	v_add_f32_e32 v89, v89, v211
	v_add_f32_e32 v86, v86, v208
	v_add_f32_e32 v87, v87, v209
	v_add_f32_e32 v84, v84, v206
	v_add_f32_e32 v85, v85, v207
	ds_read2_b32 v[196:197], v194 offset0:48 offset1:49
	ds_read2_b32 v[198:199], v194 offset0:50 offset1:51
	ds_read2_b32 v[200:201], v194 offset0:56 offset1:57
	ds_read2_b32 v[202:203], v194 offset0:58 offset1:59
	ds_read2_b32 v[204:205], v194 offset0:32 offset1:33
	ds_read2_b32 v[206:207], v194 offset0:34 offset1:35
	ds_read2_b32 v[208:209], v194 offset0:40 offset1:41
	ds_read2_b32 v[210:211], v194 offset0:42 offset1:43
	s_waitcnt lgkmcnt(4)
	v_add_f32_e32 v80, v80, v202
	v_add_f32_e32 v81, v81, v203
	v_add_f32_e32 v78, v78, v200
	v_add_f32_e32 v79, v79, v201
	v_add_f32_e32 v76, v76, v198
	v_add_f32_e32 v77, v77, v199
	v_add_f32_e32 v74, v74, v196
	v_add_f32_e32 v75, v75, v197
	s_waitcnt lgkmcnt(0)
	v_add_f32_e32 v72, v72, v210
	v_add_f32_e32 v73, v73, v211
	v_add_f32_e32 v70, v70, v208
	v_add_f32_e32 v71, v71, v209
	v_add_f32_e32 v68, v68, v206
	v_add_f32_e32 v69, v69, v207
	v_add_f32_e32 v66, v66, v204
	v_add_f32_e32 v67, v67, v205

.Lattn_back_b:
	ds_read_b128 v[126:129], v186 offset:32768
	ds_read_b128 v[130:133], v186 offset:40960
	ds_read_b128 v[134:137], v187 offset:32768
	ds_read_b128 v[138:141], v187 offset:40960
	v_add_f32_e32 v98, 0, v212
	v_add_f32_e32 v98, v214, v98
	v_add_f32_e32 v98, v216, v98
	v_add_f32_e32 v98, v218, v98
	v_add_f32_e32 v98, v204, v98
	v_add_f32_e32 v98, v206, v98
	v_add_f32_e32 v98, v208, v98
	s_waitcnt lgkmcnt(3)
	v_mfma_f32_32x32x16_bf16 v[82:97], v[126:129], v[118:121], v[236:251]
	v_add_f32_e32 v98, v210, v98
	v_add_f32_e32 v98, v196, v98
	v_add_f32_e32 v98, v198, v98
	v_add_f32_e32 v98, v200, v98
	v_add_f32_e32 v98, v202, v98
	v_add_f32_e32 v98, v222, v98
	v_add_f32_e32 v98, v224, v98
	s_waitcnt lgkmcnt(2)
	v_mfma_f32_32x32x16_bf16 v[66:81], v[130:133], v[118:121], v[236:251]
	v_add_f32_e32 v98, v227, v98
	ds_read_b128 v[126:129], v188 offset:32768
	ds_read_b128 v[142:145], v188 offset:40960
	ds_read_b128 v[146:149], v189 offset:32768
	ds_read_b128 v[154:157], v189 offset:40960
	v_add_f32_e32 v98, v229, v98
	v_add_f32_e32 v98, v213, v98
	v_add_f32_e32 v98, v215, v98
	v_add_f32_e32 v98, v217, v98
	v_add_f32_e32 v98, v221, v98
	s_waitcnt lgkmcnt(5)
	v_mfma_f32_32x32x16_bf16 v[82:97], v[134:137], v[114:117], v[82:97]
	v_add_f32_e32 v98, v205, v98
	v_add_f32_e32 v98, v207, v98
	v_add_f32_e32 v98, v209, v98
	v_add_f32_e32 v98, v211, v98
	v_add_f32_e32 v98, v197, v98
	v_add_f32_e32 v98, v199, v98
	v_add_f32_e32 v98, v201, v98
	s_waitcnt lgkmcnt(4)
	v_mfma_f32_32x32x16_bf16 v[66:81], v[138:141], v[114:117], v[66:81]
	v_add_f32_e32 v98, v203, v98
	v_add_f32_e32 v98, v223, v98
	v_add_f32_e32 v98, v226, v98
	v_add_f32_e32 v98, v228, v98
	v_add_f32_e32 v98, v230, v98
	s_waitcnt lgkmcnt(3)
	v_mfma_f32_32x32x16_bf16 v[82:97], v[126:129], v[110:113], v[82:97]
	v_cvt_pk_bf16_f32 v150, v212, v214
	v_cvt_pk_bf16_f32 v151, v216, v218
	v_cvt_pk_bf16_f32 v152, v204, v206
	v_cvt_pk_bf16_f32 v153, v208, v210
	v_cvt_pk_bf16_f32 v134, v196, v198
	v_cvt_pk_bf16_f32 v135, v200, v202
	v_cvt_pk_bf16_f32 v136, v222, v224
	s_waitcnt lgkmcnt(2)
	v_mfma_f32_32x32x16_bf16 v[66:81], v[142:145], v[110:113], v[66:81]
	v_cvt_pk_bf16_f32 v137, v227, v229
	v_cvt_pk_bf16_f32 v130, v213, v215
	v_cvt_pk_bf16_f32 v131, v217, v221
	v_cvt_pk_bf16_f32 v132, v205, v207
	v_cvt_pk_bf16_f32 v133, v209, v211
	v_cvt_pk_bf16_f32 v126, v197, v199
	v_cvt_pk_bf16_f32 v127, v201, v203
	s_waitcnt lgkmcnt(1)
	v_mfma_f32_32x32x16_bf16 v[82:97], v[146:149], v[106:109], v[82:97]
	v_cvt_pk_bf16_f32 v128, v223, v226
	v_cvt_pk_bf16_f32 v129, v228, v230
	s_waitcnt lgkmcnt(0)
	v_mfma_f32_32x32x16_bf16 v[66:81], v[154:157], v[106:109], v[66:81]
	s_add_u32 s100, s12, 0xa0000
	s_addc_u32 s101, s13, 0
	global_load_dwordx4 v[138:141], v160, s[100:101] offset:2048
	global_load_dwordx4 v[142:145], v252, s[100:101]
	global_load_dwordx4 v[154:157], v161, s[100:101] offset:2048
	s_add_u32 s12, s12, 0x140000
	s_addc_u32 s13, s13, 0
	s_and_saveexec_b64 s[2:3], s[8:9]
	s_cbranch_execz .LBB0_345
	ds_read2_b32 v[196:197], v194 offset0:64 offset1:65
	ds_read2_b32 v[198:199], v194 offset0:80 offset1:81
	ds_read2_b32 v[200:201], v194 offset0:82 offset1:83
	ds_read2_b32 v[202:203], v194 offset0:88 offset1:89
	ds_read2_b32 v[204:205], v194 offset0:90 offset1:91
	ds_read2_b32 v[206:207], v194 offset0:66 offset1:67
	ds_read2_b32 v[208:209], v194 offset0:72 offset1:73
	ds_read2_b32 v[210:211], v194 offset0:74 offset1:75
	s_waitcnt lgkmcnt(7)
	v_add_f32_e32 v82, v82, v196
	v_add_f32_e32 v83, v83, v197
	s_waitcnt lgkmcnt(3)
	v_add_f32_e32 v96, v96, v204
	v_add_f32_e32 v97, v97, v205
	v_add_f32_e32 v94, v94, v202
	v_add_f32_e32 v95, v95, v203
	v_add_f32_e32 v92, v92, v200
	v_add_f32_e32 v93, v93, v201
	v_add_f32_e32 v90, v90, v198
	v_add_f32_e32 v91, v91, v199
	s_waitcnt lgkmcnt(0)
	v_add_f32_e32 v88, v88, v210
	v_add_f32_e32 v89, v89, v211
	v_add_f32_e32 v86, v86, v208
	v_add_f32_e32 v87, v87, v209
	v_add_f32_e32 v84, v84, v206
	v_add_f32_e32 v85, v85, v207
	ds_read2_b32 v[196:197], v194 offset0:112 offset1:113
	ds_read2_b32 v[198:199], v194 offset0:114 offset1:115
	ds_read2_b32 v[200:201], v194 offset0:120 offset1:121
	ds_read2_b32 v[202:203], v194 offset0:122 offset1:123
	ds_read2_b32 v[204:205], v194 offset0:96 offset1:97
	ds_read2_b32 v[206:207], v194 offset0:98 offset1:99
	ds_read2_b32 v[208:209], v194 offset0:104 offset1:105
	ds_read2_b32 v[210:211], v194 offset0:106 offset1:107
	s_waitcnt lgkmcnt(4)
	v_add_f32_e32 v80, v80, v202
	v_add_f32_e32 v81, v81, v203
	v_add_f32_e32 v78, v78, v200
	v_add_f32_e32 v79, v79, v201
	v_add_f32_e32 v76, v76, v198
	v_add_f32_e32 v77, v77, v199
	v_add_f32_e32 v74, v74, v196
	v_add_f32_e32 v75, v75, v197
	s_waitcnt lgkmcnt(0)
	v_add_f32_e32 v72, v72, v210
	v_add_f32_e32 v73, v73, v211
	v_add_f32_e32 v70, v70, v208
	v_add_f32_e32 v71, v71, v209
	v_add_f32_e32 v68, v68, v206
	v_add_f32_e32 v69, v69, v207
	v_add_f32_e32 v66, v66, v204
	v_add_f32_e32 v67, v67, v205
	s_branch .LBB0_345

.Lattn_back_t:
	v_add_f32_e32 v98, 0, v199
	ds_read_b128 v[122:125], v186 offset:49152
	ds_read_b128 v[126:129], v186 offset:57344
	ds_read_b128 v[130:133], v187 offset:49152
	ds_read_b128 v[134:137], v187 offset:57344
	ds_read_b128 v[138:141], v188 offset:49152
	ds_read_b128 v[142:145], v188 offset:57344
	v_add_f32_e32 v98, v201, v98
	v_add_f32_e32 v98, v202, v98
	v_add_f32_e32 v98, v205, v98
	v_add_f32_e32 v98, v207, v98
	v_add_f32_e32 v98, v209, v98
	s_waitcnt lgkmcnt(5)
	v_mfma_f32_32x32x16_bf16 v[82:97], v[122:125], v[118:121], v[236:251]
	v_add_f32_e32 v98, v211, v98
	v_add_f32_e32 v98, v213, v98
	v_add_f32_e32 v98, v215, v98
	v_add_f32_e32 v98, v216, v98
	v_add_f32_e32 v98, v217, v98
	v_add_f32_e32 v98, v218, v98
	v_add_f32_e32 v98, v221, v98
	s_waitcnt lgkmcnt(4)
	v_mfma_f32_32x32x16_bf16 v[66:81], v[126:129], v[118:121], v[236:251]
	v_add_f32_e32 v98, v222, v98
	v_add_f32_e32 v98, v223, v98
	v_add_f32_e32 v98, v224, v98
	v_add_f32_e32 v98, v195, v98
	v_add_f32_e32 v98, v196, v98
	v_add_f32_e32 v98, v197, v98
	v_add_f32_e32 v98, v198, v98
	s_waitcnt lgkmcnt(3)
	v_mfma_f32_32x32x16_bf16 v[82:97], v[130:133], v[114:117], v[82:97]
	v_add_f32_e32 v98, v200, v98
	ds_read_b128 v[146:149], v189 offset:49152
	ds_read_b128 v[154:157], v189 offset:57344
	v_add_f32_e32 v98, v203, v98
	v_add_f32_e32 v98, v204, v98
	v_add_f32_e32 v98, v206, v98
	v_add_f32_e32 v98, v208, v98
	v_add_f32_e32 v98, v210, v98
	s_waitcnt lgkmcnt(4)
	v_mfma_f32_32x32x16_bf16 v[66:81], v[134:137], v[114:117], v[66:81]
	v_add_f32_e32 v98, v212, v98
	v_add_f32_e32 v98, v214, v98
	v_add_f32_e32 v98, v150, v98
	v_add_f32_e32 v98, v151, v98
	v_add_f32_e32 v98, v152, v98
	v_add_f32_e32 v100, v153, v98
	v_mov_b32_e32 v122, v100
	s_waitcnt lgkmcnt(3)
	v_mfma_f32_32x32x16_bf16 v[82:97], v[138:141], v[110:113], v[82:97]
	v_permlane32_swap_b32_e32 v100, v122
	v_cvt_pk_bf16_f32 v114, v199, v201
	v_cvt_pk_bf16_f32 v115, v202, v205
	v_cvt_pk_bf16_f32 v116, v207, v209
	v_cvt_pk_bf16_f32 v117, v211, v213
	s_waitcnt lgkmcnt(2)
	v_mfma_f32_32x32x16_bf16 v[66:81], v[142:145], v[110:113], v[66:81]
	v_cvt_pk_bf16_f32 v110, v215, v216
	v_cvt_pk_bf16_f32 v111, v217, v218
	v_cvt_pk_bf16_f32 v112, v221, v222
	v_cvt_pk_bf16_f32 v113, v223, v224
	v_cvt_pk_bf16_f32 v118, v195, v196
	v_cvt_pk_bf16_f32 v119, v197, v198
	v_cvt_pk_bf16_f32 v120, v200, v203
	s_waitcnt lgkmcnt(1)
	v_mfma_f32_32x32x16_bf16 v[82:97], v[146:149], v[106:109], v[82:97]
	v_cvt_pk_bf16_f32 v121, v204, v206
	s_waitcnt lgkmcnt(0)
	v_mfma_f32_32x32x16_bf16 v[66:81], v[154:157], v[106:109], v[66:81]
	v_cvt_pk_bf16_f32 v106, v208, v210
	v_cvt_pk_bf16_f32 v107, v212, v214
	v_cvt_pk_bf16_f32 v108, v150, v151
	v_cvt_pk_bf16_f32 v109, v152, v153
	s_and_saveexec_b64 s[2:3], s[8:9]
	s_cbranch_execz .LBB0_352
	v_sub_u32_e32 v98, s79, v178
	v_lshlrev_b32_e32 v98, 2, v98
	v_lshlrev_b32_e32 v101, 2, v179
	v_add3_u32 v98, s1, v98, v101
	ds_read2_b32 v[124:125], v98 offset0:240 offset1:241
	ds_read2_b32 v[126:127], v98 offset0:242 offset1:243
	ds_read2_b32 v[128:129], v98 offset0:248 offset1:249
	ds_read2_b32 v[130:131], v98 offset0:250 offset1:251
	ds_read2_b32 v[132:133], v98 offset0:224 offset1:225
	ds_read2_b32 v[134:135], v98 offset0:226 offset1:227
	ds_read2_b32 v[136:137], v98 offset0:232 offset1:233
	ds_read2_b32 v[138:139], v98 offset0:234 offset1:235
	s_waitcnt lgkmcnt(4)
	v_add_f32_e32 v96, v96, v130
	v_add_f32_e32 v97, v97, v131
	v_add_f32_e32 v94, v94, v128
	v_add_f32_e32 v95, v95, v129
	v_add_f32_e32 v92, v92, v126
	v_add_f32_e32 v93, v93, v127
	v_add_f32_e32 v90, v90, v124
	v_add_f32_e32 v91, v91, v125
	s_waitcnt lgkmcnt(0)
	v_add_f32_e32 v88, v88, v138
	v_add_f32_e32 v89, v89, v139
	v_add_f32_e32 v86, v86, v136
	v_add_f32_e32 v87, v87, v137
	v_add_f32_e32 v84, v84, v134
	v_add_f32_e32 v85, v85, v135
	v_add_f32_e32 v82, v82, v132
	v_add_f32_e32 v83, v83, v133
	v_add_u32_e32 v136, 0x420, v98
	v_add_u32_e32 v138, 0x428, v98
	v_add_u32_e32 v124, 0x440, v98
	v_add_u32_e32 v126, 0x448, v98
	v_add_u32_e32 v128, 0x460, v98
	v_add_u32_e32 v101, 0x400, v98
	v_add_u32_e32 v123, 0x408, v98
	v_add_u32_e32 v98, 0x468, v98
	ds_read2_b32 v[124:125], v124 offset1:1
	ds_read2_b32 v[126:127], v126 offset1:1
	ds_read2_b32 v[128:129], v128 offset1:1
	ds_read2_b32 v[130:131], v98 offset1:1
	ds_read2_b32 v[132:133], v101 offset1:1
	ds_read2_b32 v[134:135], v123 offset1:1
	ds_read2_b32 v[136:137], v136 offset1:1
	ds_read2_b32 v[138:139], v138 offset1:1
	s_waitcnt lgkmcnt(4)
	v_add_f32_e32 v80, v80, v130
	v_add_f32_e32 v81, v81, v131
	v_add_f32_e32 v78, v78, v128
	v_add_f32_e32 v79, v79, v129
	v_add_f32_e32 v76, v76, v126
	v_add_f32_e32 v77, v77, v127
	v_add_f32_e32 v74, v74, v124
	v_add_f32_e32 v75, v75, v125
	s_waitcnt lgkmcnt(0)
	v_add_f32_e32 v72, v72, v138
	v_add_f32_e32 v73, v73, v139
	v_add_f32_e32 v70, v70, v136
	v_add_f32_e32 v71, v71, v137
	v_add_f32_e32 v68, v68, v134
	v_add_f32_e32 v69, v69, v135
	v_add_f32_e32 v66, v66, v132
	v_add_f32_e32 v67, v67, v133
